# attention unit prologue: tile-1 and K(2) global loads issued right behind the tile-0 loads (one exposed global latency per unit removed), counted vmcnt
# baseline (speedup 1.0000x reference)
; __device__ __forceinline__ int v_st(int k, int c) { const int kk = (k & ~0xC) | ((k & 4) << 1) | ((k & 8) >> 1); return ((kk >> 3) * 4 + (c >> 5)) * 512 + ((kk & 7) * 32 + (c & 31)) * 2; }
; __device__ __forceinline__ int v_rd_base(int lane) { return ((lane & 3) << 3) | (((lane >> 2) & 3) << 6) | (((lane >> 4) & 1) << 5) | (((lane >> 5) & 1) << 8); }
; #define SLOAD(i, k0) do { sr_[i].vs0 = *reinterpret_cast<const bf16x8*>(&Vh[(long)((k0) + sr) * LDQ + sc]); sr_[i].vs1 = *reinterpret_cast<const bf16x8*>(&Vh[(long)((k0) + 32 + sr) * LDQ + sc]); \
;     sr_[i].ks0 = *reinterpret_cast<const bf16x8*>(&Kh[(long)((k0) + kr) * LDQ + kc]); } while (0)
; __device__ __forceinline__ void partialSM(f32x16& p0, f32x16& p1, float& m_ref, float& alpha, bool first) {
;   constexpr float THRL = THR * 1.4426950408889634f;
;   float pmax = p0[0];
; #pragma unroll
;   for (int r = 1; r < 16; ++r) pmax = fmaxf(pmax, p0[r]);
; #pragma unroll
;   for (int r = 0; r < 16; ++r) pmax = fmaxf(pmax, p1[r]);
;   { auto rr = __builtin_amdgcn_permlane32_swap(__float_as_uint(pmax), __float_as_uint(pmax), false, false);
;     pmax = fmaxf(__uint_as_float(rr[0]), __uint_as_float(rr[1])); }
; __device__ __forceinline__ void attn_unit(const bf16_t* __restrict__ Qb, const bf16_t* __restrict__ Kh, const bf16_t* __restrict__ Vh, int seq, char* lds,
;                                           int mode, float* scratch, float lam, float gscale, const float* __restrict__ subg, bf16_t* outp) {
;     ...
;   const bf16_t* Qw = Qb + (long)(wid * QBLK + r32) * LDQ + hi * 8;
; #pragma unroll
;   for (int d0 = 0; d0 < 4; ++d0) qr[d0] = *reinterpret_cast<const bf16x8*>(Qw + d0 * 16);
;   const int sr = tid >> 4, sc = (tid & 15) * 8, vst0 = v_st(sr, sc), vst1 = v_st(32 + sr, sc);
;   const int kr = tid >> 3, kc = (tid & 7) * 8, kst = KSWZ(kr, kc * 2);
;   const int vb0 = (int)(uintptr_t)V_lds + v_rd_base(lane);
;   struct { bf16x8 vs0, vs1, ks0; } sr_[2];
;     ...
;   f32x16 pA0, pA1, pB0, pB1; float alA, alB; bf16x8 pa0, pa1, pa2, pa3; const int NT = seq / KVBLK;
;   constexpr int SE = 0, SO = 1;
;   SLOAD(SE, 0); asm volatile("s_waitcnt vmcnt(0)" ::: "memory"); SWRITE(0, SE); __syncthreads();
;   qkt(pA0, pA1, K_lds, qr, r32, hi, m_reg); partialSM(pA0, pA1, m_reg, alA, true);
;   SLOAD(SO, KVBLK); if (2 < NT) SLOAD(SE, 2 * KVBLK);
;   SWAIT(); SWRITE(1, SO); __syncthreads();
.LBB0_1329:
	v_mov_b32_e32 v56, v214
	s_or_b32 s52, s24, s76
	v_ashrrev_i32_e32 v57, 6, v56
	v_and_b32_e32 v165, 31, v56
	v_lshlrev_b32_e32 v152, 5, v57
	s_lshl_b64 s[0:1], s[52:53], 1
	v_or_b32_e32 v0, v152, v165
	s_add_u32 s58, s74, s0
	v_ashrrev_i32_e32 v1, 31, v0
	s_addc_u32 s59, s75, s1
	v_bfe_u32 v164, v56, 5, 1
	v_lshlrev_b64 v[0:1], 10, v[0:1]
	v_lshl_add_u64 v[0:1], s[58:59], 0, v[0:1]
	v_lshlrev_b32_e32 v178, 4, v164
	v_lshl_add_u64 v[0:1], v[0:1], 0, v[178:179]
	global_load_dwordx4 v[124:127], v[0:1], off
	global_load_dwordx4 v[120:123], v[0:1], off offset:32
	global_load_dwordx4 v[116:119], v[0:1], off offset:64
	global_load_dwordx4 v[112:115], v[0:1], off offset:96
	v_ashrrev_i32_e32 v0, 4, v56
	v_and_b32_e32 v1, 0xfffff0, v0
	v_lshlrev_b32_e32 v3, 1, v0
	v_lshlrev_b32_e32 v12, 3, v56
	v_and_or_b32 v1, v3, 8, v1
	v_lshrrev_b32_e32 v3, 1, v0
	v_lshrrev_b32_e32 v1, 1, v1
	v_bfe_u32 v5, v12, 5, 2
	v_and_b32_e32 v4, 3, v0
	v_or_b32_e32 v1, v1, v5
	v_and_or_b32 v3, v3, 4, v4
	v_lshlrev_b32_e32 v6, 4, v56
	v_lshlrev_b32_e32 v1, 9, v1
	v_lshlrev_b32_e32 v3, 6, v3
	v_and_b32_e32 v7, 48, v6
	v_add_u32_e32 v4, 32, v0
	v_or3_b32 v168, v1, v3, v7
	v_and_b32_e32 v1, 0xfffff0, v4
	v_lshlrev_b32_e32 v8, 1, v4
	v_and_or_b32 v1, v8, 8, v1
	v_lshrrev_b32_e32 v1, 1, v1
	v_or_b32_e32 v1, v1, v5
	v_lshlrev_b32_e32 v1, 9, v1
	v_ashrrev_i32_e32 v8, 3, v56
	v_or3_b32 v169, v1, v3, v7
	v_lshrrev_b32_e32 v232, 7, v56
	v_lshlrev_b32_e32 v232, 11, v232
	v_bfe_u32 v233, v56, 2, 2
	v_lshl_or_b32 v232, v233, 9, v232
	v_bfe_u32 v233, v56, 4, 3
	v_lshl_or_b32 v232, v233, 6, v232
	v_and_b32_e32 v233, 3, v56
	v_lshl_or_b32 v168, v233, 4, v232
	v_add_u32_e32 v169, 0x2000, v168
	v_lshlrev_b32_e32 v1, 7, v8
	v_and_b32_e32 v10, 0x70, v6
	v_and_b32_e32 v3, 0x70, v56
	v_bitop3_b32 v170, v10, v1, v3 bitop3:0xde
	v_ashrrev_i32_e32 v1, 31, v0
	v_ashrrev_i32_e32 v5, 31, v4
	s_add_u32 s20, s77, s0
	v_and_b32_e32 v2, 0x78, v12
	v_lshlrev_b64 v[48:49], 10, v[0:1]
	v_lshlrev_b64 v[4:5], 10, v[4:5]
	v_ashrrev_i32_e32 v9, 31, v8
	s_addc_u32 s21, s78, s1
	v_lshl_add_u64 v[0:1], s[18:19], 0, v[48:49]
	v_lshlrev_b32_e32 v6, 1, v2
	v_mov_b32_e32 v7, v179
	v_lshl_add_u64 v[4:5], s[18:19], 0, v[4:5]
	v_lshlrev_b64 v[50:51], 10, v[8:9]
	v_lshl_add_u64 v[52:53], v[0:1], 0, v[6:7]
	v_lshl_add_u64 v[4:5], v[4:5], 0, v[6:7]
	v_lshl_add_u64 v[8:9], s[20:21], 0, v[50:51]
	v_mov_b32_e32 v11, v179
	global_load_dwordx4 v[0:3], v[52:53], off
	v_lshl_add_u64 v[54:55], v[8:9], 0, v[10:11]
	global_load_dwordx4 v[4:7], v[4:5], off
	v_lshlrev_b32_e32 v64, 7, v165
	global_load_dwordx4 v[8:11], v[54:55], off
	v_add_co_u32_e32 v140, vcc, 0x10000, v52
	s_nop 0
	v_addc_co_u32_e32 v141, vcc, 0, v53, vcc
	v_add_co_u32_e32 v144, vcc, 0x18000, v52
	s_nop 0
	v_addc_co_u32_e32 v145, vcc, 0, v53, vcc
	v_add_co_u32_e32 v148, vcc, 0x10000, v54
	s_nop 0
	v_addc_co_u32_e32 v149, vcc, 0, v55, vcc
	v_add_co_u32_e32 v136, vcc, 0x20000, v54
	s_nop 0
	v_addc_co_u32_e32 v137, vcc, 0, v55, vcc
	global_load_dwordx4 v[140:143], v[140:141], off
	global_load_dwordx4 v[144:147], v[144:145], off
	global_load_dwordx4 v[148:151], v[148:149], off
	global_load_dwordx4 v[136:139], v[136:137], off
	v_and_b32_e32 v65, 0x70, v12
	v_add_u32_e32 v58, 0, v168
	v_add_u32_e32 v59, 0, v169
	v_bitop3_b32 v173, v178, v64, v65 bitop3:0xde
	s_waitcnt vmcnt(4)
	v_add_u32_e32 v171, 0, v170
	v_mov_b64_e32 v[32:33], s[36:37]
	v_mov_b64_e32 v[34:35], s[38:39]
	v_mov_b64_e32 v[36:37], s[40:41]
	v_mov_b64_e32 v[38:39], s[42:43]
	v_mov_b64_e32 v[40:41], s[44:45]
	v_mov_b64_e32 v[42:43], s[46:47]
	v_mov_b64_e32 v[44:45], s[48:49]
	v_mov_b64_e32 v[46:47], s[50:51]
	s_mov_b32 s0, 0x18000
	s_waitcnt vmcnt(6)
	ds_write_b128 v58, v[0:3]
	s_waitcnt vmcnt(5)
	ds_write_b128 v59, v[4:7]
	v_add_u32_e32 v4, 0, v173
	s_waitcnt vmcnt(4)
	ds_write_b128 v171, v[8:11] offset:49152
	s_waitcnt lgkmcnt(0)
	s_barrier
	ds_read_b128 v[0:3], v4 offset:49152
	ds_read_b128 v[60:63], v4 offset:53248
	s_waitcnt lgkmcnt(1)
	v_mfma_f32_32x32x16_bf16 v[16:31], v[0:3], v[124:127], v[32:47]
	s_waitcnt lgkmcnt(0)
	v_mfma_f32_32x32x16_bf16 v[0:15], v[60:63], v[124:127], v[32:47]
	s_nop 6
	v_or_b32_e32 v32, 32, v178
	v_bitop3_b32 v175, v32, v64, v65 bitop3:0xde
	v_add_u32_e32 v36, 0, v175
	ds_read_b128 v[32:35], v36 offset:49152
	ds_read_b128 v[36:39], v36 offset:53248
	s_waitcnt lgkmcnt(1)
	v_mfma_f32_32x32x16_bf16 v[16:31], v[32:35], v[120:123], v[16:31]
	v_or_b32_e32 v32, 64, v178
	v_bitop3_b32 v174, v32, v64, v65 bitop3:0xde
	s_waitcnt lgkmcnt(0)
	v_mfma_f32_32x32x16_bf16 v[0:15], v[36:39], v[120:123], v[0:15]
	v_add_u32_e32 v36, 0, v174
	ds_read_b128 v[32:35], v36 offset:49152
	ds_read_b128 v[36:39], v36 offset:53248
	s_waitcnt lgkmcnt(1)
	v_mfma_f32_32x32x16_bf16 v[16:31], v[32:35], v[116:119], v[16:31]
	v_or_b32_e32 v32, 0x60, v178
	v_bitop3_b32 v176, v32, v64, v65 bitop3:0xde
	s_waitcnt lgkmcnt(0)
	v_mfma_f32_32x32x16_bf16 v[0:15], v[36:39], v[116:119], v[0:15]
	v_add_u32_e32 v36, 0, v176
	ds_read_b128 v[32:35], v36 offset:49152
	ds_read_b128 v[36:39], v36 offset:53248
	s_waitcnt lgkmcnt(1)
	v_mfma_f32_32x32x16_bf16 v[16:31], v[32:35], v[112:115], v[16:31]
	s_waitcnt lgkmcnt(0)
	v_mfma_f32_32x32x16_bf16 v[0:15], v[36:39], v[112:115], v[0:15]
	s_nop 9
	v_max_f32_e32 v32, v17, v17
	v_max_f32_e32 v33, v16, v16
	v_max_f32_e32 v32, v33, v32
	v_max3_f32 v32, v32, v18, v19
	v_max3_f32 v32, v32, v20, v21
	v_max3_f32 v32, v32, v22, v23
	v_max3_f32 v32, v32, v24, v25
	v_max3_f32 v32, v32, v26, v27
	v_max3_f32 v32, v32, v28, v29
	v_max3_f32 v32, v32, v30, v31
	v_max3_f32 v32, v32, v0, v1
	v_max3_f32 v32, v32, v2, v3
	v_max3_f32 v32, v32, v4, v5
	v_max3_f32 v32, v32, v6, v7
	v_max3_f32 v32, v32, v8, v9
	v_max3_f32 v32, v32, v10, v11
	v_max3_f32 v32, v32, v12, v13
	v_max3_f32 v36, v32, v14, v15
	v_mov_b32_e32 v37, v36
	s_mov_b32 s0, 0x20000
	s_nop 1
	v_permlane32_swap_b32_e32 v36, v37


; __device__ __forceinline__ int v_st(int k, int c) { const int kk = (k & ~0xC) | ((k & 4) << 1) | ((k & 8) >> 1); return ((kk >> 3) * 4 + (c >> 5)) * 512 + ((kk & 7) * 32 + (c & 31)) * 2; }
; __device__ __forceinline__ int v_rd_base(int lane) { return ((lane & 3) << 3) | (((lane >> 2) & 3) << 6) | (((lane >> 4) & 1) << 5) | (((lane >> 5) & 1) << 8); }
; #define SLOAD(i, k0) do { sr_[i].vs0 = *reinterpret_cast<const bf16x8*>(&Vh[(long)((k0) + sr) * LDQ + sc]); sr_[i].vs1 = *reinterpret_cast<const bf16x8*>(&Vh[(long)((k0) + 32 + sr) * LDQ + sc]); \
;     sr_[i].ks0 = *reinterpret_cast<const bf16x8*>(&Kh[(long)((k0) + kr) * LDQ + kc]); } while (0)
; __device__ __forceinline__ void partialSM(f32x16& p0, f32x16& p1, float& m_ref, float& alpha, bool first) {
;     ...
;   else { const float dl = first ? pmax : fmaxf(pmax, 0.f); m_ref += dl; alpha = first ? 1.f : __builtin_amdgcn_exp2f(-dl);
; #pragma unroll
;     for (int r = 0; r < 16; ++r) { p0[r] -= dl; p1[r] -= dl; } }
; #pragma unroll
;   for (int r = 0; r < 16; ++r) p0[r] = __builtin_amdgcn_exp2f(p0[r]);
; __device__ __forceinline__ void attn_unit(const bf16_t* __restrict__ Qb, const bf16_t* __restrict__ Kh, const bf16_t* __restrict__ Vh, int seq, char* lds,
;                                           int mode, float* scratch, float lam, float gscale, const float* __restrict__ subg, bf16_t* outp) {
;     ...
;   float m_reg = 0.f, l_reg = 0; f32x16 o[4] = {}; bf16x8 qr[4];
;   const bf16_t* Qw = Qb + (long)(wid * QBLK + r32) * LDQ + hi * 8;
; #pragma unroll
;   for (int d0 = 0; d0 < 4; ++d0) qr[d0] = *reinterpret_cast<const bf16x8*>(Qw + d0 * 16);
;   const int sr = tid >> 4, sc = (tid & 15) * 8, vst0 = v_st(sr, sc), vst1 = v_st(32 + sr, sc);
;   const int kr = tid >> 3, kc = (tid & 7) * 8, kst = KSWZ(kr, kc * 2);
;   const int vb0 = (int)(uintptr_t)V_lds + v_rd_base(lane);
;   struct { bf16x8 vs0, vs1, ks0; } sr_[2];
;     ...
;   f32x16 pA0, pA1, pB0, pB1; float alA, alB; bf16x8 pa0, pa1, pa2, pa3; const int NT = seq / KVBLK;
;   constexpr int SE = 0, SO = 1;
;   SLOAD(SE, 0); asm volatile("s_waitcnt vmcnt(0)" ::: "memory"); SWRITE(0, SE); __syncthreads();
;   qkt(pA0, pA1, K_lds, qr, r32, hi, m_reg); partialSM(pA0, pA1, m_reg, alA, true);
;   SLOAD(SO, KVBLK); if (2 < NT) SLOAD(SE, 2 * KVBLK);
;   SWAIT(); SWRITE(1, SO); __syncthreads();
;   int bp = 0, bc = 1, bn = 2;
;     ...
;   if (wid >= 4) __builtin_amdgcn_s_setprio(1);
	s_waitcnt vmcnt(1)
	v_cmp_lt_i32_e32 vcc, 3, v57
	s_nop 0
	ds_write_b128 v58, v[140:143] offset:16384
	s_nop 0
	ds_write_b128 v59, v[144:147] offset:16384
	ds_write_b128 v171, v[148:151] offset:57344
	s_waitcnt lgkmcnt(0)
	s_barrier
	s_and_saveexec_b64 s[20:21], vcc
	s_setprio 1
	s_or_b64 exec, exec, s[20:21]
	v_max_f32_e32 v33, v37, v37
	v_max_f32_e32 v34, v36, v36
	v_max_f32_e32 v33, v34, v33
	s_xor_b64 s[72:73], s[4:5], -1
	s_add_i32 s1, 0, 0x14000
	v_sub_f32_e32 v64, v0, v33
	v_and_b32_e32 v0, 15, v56
	v_and_b32_e32 v32, 63, v56
	v_sub_f32_e32 v16, v16, v33
	v_sub_f32_e32 v17, v17, v33
	s_cmp_lg_u32 0, -1
	v_sub_f32_e32 v65, v1, v33
	v_lshlrev_b32_e32 v0, 4, v0
	v_mov_b32_e32 v1, v179
	v_sub_f32_e32 v18, v18, v33
	v_exp_f32_e32 v160, v16
	v_exp_f32_e32 v192, v17
	v_and_b32_e32 v16, 0x3fffffc0, v56
	v_lshlrev_b32_e32 v17, 4, v32
	s_cselect_b32 s4, 0, 0
	v_lshl_add_u64 v[0:1], v[48:49], 0, v[0:1]
	s_add_i32 s52, s71, s24
	v_sub_f32_e32 v19, v19, v33
	v_sub_f32_e32 v20, v20, v33
	v_sub_f32_e32 v21, v21, v33
	v_sub_f32_e32 v22, v22, v33
	v_sub_f32_e32 v23, v23, v33
	v_sub_f32_e32 v24, v24, v33
	v_sub_f32_e32 v25, v25, v33
	v_sub_f32_e32 v26, v26, v33
	v_sub_f32_e32 v27, v27, v33
	v_sub_f32_e32 v28, v28, v33
	v_sub_f32_e32 v29, v29, v33
	v_sub_f32_e32 v30, v30, v33
	v_sub_f32_e32 v31, v31, v33
	v_exp_f32_e32 v151, v18
	v_lshl_add_u32 v166, v16, 2, s1
	v_lshlrev_b32_e32 v16, 3, v32
	v_and_b32_e32 v17, 0xc0, v17
	v_lshlrev_b32_e32 v18, 1, v32
	v_lshl_add_u64 v[154:155], s[28:29], 0, v[0:1]
	v_and_b32_e32 v0, 7, v56
	s_lshl_b64 s[20:21], s[52:53], 1
	v_exp_f32_e32 v161, v19
	v_exp_f32_e32 v149, v20
	v_exp_f32_e32 v159, v21
	v_exp_f32_e32 v148, v22
	v_exp_f32_e32 v150, v23
	v_exp_f32_e32 v145, v24
	v_exp_f32_e32 v147, v25
	v_exp_f32_e32 v143, v26
	v_exp_f32_e32 v146, v27
	v_exp_f32_e32 v141, v28
	v_exp_f32_e32 v144, v29
	v_exp_f32_e32 v140, v30
	v_exp_f32_e32 v142, v31
	v_and_or_b32 v17, v16, 24, v17
	v_and_b32_e32 v18, 32, v18
	v_and_b32_e32 v16, 0x100, v16
	v_lshlrev_b32_e32 v0, 4, v0
	v_mov_b32_e32 v1, v179
	s_add_u32 s20, s10, s20
	v_or3_b32 v16, v17, v18, v16
	v_sub_f32_e32 v79, v15, v33
	v_sub_f32_e32 v78, v14, v33
	v_lshl_add_u64 v[0:1], v[50:51], 0, v[0:1]
	s_addc_u32 s21, s11, s21
	v_mov_b32_e32 v14, v179
	v_mov_b32_e32 v15, v179
	v_add_u32_e32 v177, s4, v16
	v_add_f32_e32 v181, 0, v33
	v_sub_f32_e32 v77, v13, v33
	v_sub_f32_e32 v76, v12, v33
	v_sub_f32_e32 v75, v11, v33
	v_sub_f32_e32 v74, v10, v33
	v_sub_f32_e32 v73, v9, v33
	v_sub_f32_e32 v72, v8, v33
	v_sub_f32_e32 v71, v7, v33
	v_sub_f32_e32 v70, v6, v33
	v_sub_f32_e32 v69, v5, v33
	v_sub_f32_e32 v68, v4, v33
	v_sub_f32_e32 v67, v3, v33
	v_sub_f32_e32 v66, v2, v33
	v_cmp_gt_u32_e64 s[4:5], 32, v32
	v_lshl_add_u64 v[156:157], s[20:21], 0, v[0:1]
	v_mov_b32_e32 v0, v179
	v_mov_b32_e32 v1, v179
	v_mov_b32_e32 v2, v179
	v_mov_b32_e32 v3, v179
	v_mov_b32_e32 v4, v179
	v_mov_b32_e32 v5, v179
	v_mov_b32_e32 v6, v179
	v_mov_b32_e32 v7, v179
	v_mov_b32_e32 v8, v179
	v_mov_b32_e32 v9, v179
	v_mov_b32_e32 v10, v179
	v_mov_b32_e32 v11, v179
	v_mov_b32_e32 v12, v179
	v_mov_b32_e32 v13, v179
	v_mov_b64_e32 v[62:63], v[14:15]
	v_mov_b64_e32 v[46:47], v[14:15]
	v_mov_b64_e32 v[30:31], v[14:15]
	s_mov_b32 s0, 2
	s_mov_b32 s1, 1
	s_mov_b32 s2, 0
	v_lshl_add_u32 v153, v165, 2, v166
	v_mov_b32_e32 v167, 0
	v_mov_b32_e32 v186, 1.0
	v_mov_b64_e32 v[60:61], v[12:13]
	v_mov_b64_e32 v[58:59], v[10:11]
	v_mov_b64_e32 v[56:57], v[8:9]
	v_mov_b64_e32 v[54:55], v[6:7]
	v_mov_b64_e32 v[52:53], v[4:5]
	v_mov_b64_e32 v[50:51], v[2:3]
	v_mov_b64_e32 v[48:49], v[0:1]
	v_mov_b64_e32 v[44:45], v[12:13]
	v_mov_b64_e32 v[42:43], v[10:11]
	v_mov_b64_e32 v[40:41], v[8:9]
	v_mov_b64_e32 v[38:39], v[6:7]
	v_mov_b64_e32 v[36:37], v[4:5]
	v_mov_b64_e32 v[34:35], v[2:3]
	v_mov_b64_e32 v[32:33], v[0:1]
	v_mov_b64_e32 v[28:29], v[12:13]
	v_mov_b64_e32 v[26:27], v[10:11]
	v_mov_b64_e32 v[24:25], v[8:9]
	v_mov_b64_e32 v[22:23], v[6:7]
	v_mov_b64_e32 v[20:21], v[4:5]
	v_mov_b64_e32 v[18:19], v[2:3]
	v_mov_b64_e32 v[16:17], v[0:1]
	s_mov_b32 s52, 1
	v_exp_f32_e32 v80, v64
	v_exp_f32_e32 v81, v65
	v_exp_f32_e32 v82, v66
	v_exp_f32_e32 v83, v67
	v_exp_f32_e32 v84, v68
	v_exp_f32_e32 v85, v69
	v_exp_f32_e32 v86, v70
	v_exp_f32_e32 v87, v71
	v_exp_f32_e32 v88, v72
	v_exp_f32_e32 v89, v73
	v_exp_f32_e32 v90, v74
	v_exp_f32_e32 v91, v75
	v_exp_f32_e32 v92, v76
	v_exp_f32_e32 v93, v77
	v_exp_f32_e32 v94, v78
	v_exp_f32_e32 v95, v79
	v_mov_b32_e32 v64, v160
	v_mov_b32_e32 v65, v192
	v_mov_b32_e32 v66, v151
	v_mov_b32_e32 v67, v161
	v_mov_b32_e32 v68, v149
	v_mov_b32_e32 v69, v159
	v_mov_b32_e32 v70, v148
	v_mov_b32_e32 v71, v150
	v_mov_b32_e32 v72, v145
	v_mov_b32_e32 v73, v147
	v_mov_b32_e32 v74, v143
	v_mov_b32_e32 v75, v146
	v_mov_b32_e32 v76, v141
	v_mov_b32_e32 v77, v144
	v_mov_b32_e32 v78, v140
	v_mov_b32_e32 v79, v142
	v_mov_b32_e32 v235, v186
	v_readfirstlane_b32 s24, v156
	v_readfirstlane_b32 s25, v157
	v_readfirstlane_b32 s79, v214
	v_readfirstlane_b32 s58, v154
	s_nop 3
	s_lshr_b32 s79, s79, 6
	s_lshl_b32 s20, s79, 13
	s_sub_u32 s24, s24, s20
	s_subb_u32 s25, s25, 0
	s_lshl_b32 s20, s79, 12
	s_sub_i32 s58, s58, s20
	s_sub_i32 s58, s58, s24
	s_add_i32 s58, s58, 0x2000000
	s_lshl_b32 s79, s79, 10
	s_add_u32 s24, s24, s16
	s_addc_u32 s25, s25, s17
	s_add_u32 s24, s24, 0x15c20000
	s_addc_u32 s25, s25, 0
	v_lshrrev_b32_e32 v217, 6, v214
	v_lshlrev_b32_e32 v217, 13, v217
	v_bfe_u32 v218, v214, 2, 3
	v_lshl_add_u32 v217, v218, 10, v217
	v_bfe_u32 v218, v214, 5, 1
	v_lshl_add_u32 v217, v218, 6, v217
	v_and_b32_e32 v218, 3, v214
	v_lshl_add_u32 v217, v218, 4, v217
	v_add_u32_e32 v233, s58, v217
	v_add_u32_e32 v234, 0x80, v233
	v_lshrrev_b32_e32 v217, 3, v214
	v_lshlrev_b32_e32 v217, 10, v217
	v_bfe_u32 v218, v214, 4, 3
	v_and_b32_e32 v232, 7, v214
	v_xor_b32_e32 v232, v232, v218
	v_lshl_add_u32 v232, v232, 4, v217
	v_add_u32_e32 v217, 0x10000, v232
	v_add_u32_e32 v232, 0x20000, v232
	s_waitcnt vmcnt(0)
	v_add_u32_e32 v218, 0x4000, v170
	ds_write_b128 v218, v[136:139] offset:49152
	s_add_i32 m0, s79, 0x12000
	s_nop 0
	global_load_lds_dwordx4 v217, s[24:25]
	v_readfirstlane_b32 s58, v214
	s_setprio 0
	s_lshr_b32 s58, s58, 8
	s_cmp_lg_u32 s58, 0
	s_cbranch_scc1 .Lat_noprio
	s_setprio 1
